# gemm_out K loop: A/B fragments read several ahead into spare VGPR quads with counted lgkmcnt instead of eight read-wait-MFMA round trips per K step (on top of the gemm_in last-step change)
# speedup vs baseline: 1.0059x; 1.0005x over previous
.LBB0_62:
	s_add_i32 s2, s50, 0xffff8000
	s_and_b32 s2, s2, 0x8000
	v_add_u32_e32 v110, s2, v102
	v_add_u32_e32 v126, v110, v104
	v_add_u32_e32 v127, v110, v103
	ds_read_b128 v[106:109], v126 offset:16384
	ds_read_b128 v[110:113], v126 offset:18432
	ds_read_b128 v[114:117], v126 offset:20480
	ds_read_b128 v[118:121], v126 offset:22528
	ds_read_b128 v[122:125], v127
	ds_read_b128 v[164:167], v127 offset:2048
	ds_read_b128 v[168:171], v127 offset:4096
	ds_read_b128 v[234:237], v127 offset:6144
	ds_read_b128 v[238:241], v126 offset:17408
	ds_read_b128 v[250:253], v126 offset:19456
	s_add_i32 s50, s50, 0x8000
	s_add_u32 s42, s42, 0x80
	s_addc_u32 s43, s43, 0
	s_waitcnt lgkmcnt(5)
	v_mfma_f32_16x16x32_bf16 v[46:49], v[106:109], v[122:125], v[46:49]
	s_add_i32 s51, s51, 64
	s_add_i32 s44, s44, 1
	s_cmpk_eq_i32 s42, 0x480
	v_mfma_f32_16x16x32_bf16 v[50:53], v[110:113], v[122:125], v[50:53]
	v_mfma_f32_16x16x32_bf16 v[58:61], v[114:117], v[122:125], v[58:61]
	v_mfma_f32_16x16x32_bf16 v[62:65], v[118:121], v[122:125], v[62:65]
	ds_read_b128 v[122:125], v126 offset:21504
	s_waitcnt lgkmcnt(5)
	v_mfma_f32_16x16x32_bf16 v[54:57], v[106:109], v[164:167], v[54:57]
	v_mfma_f32_16x16x32_bf16 v[34:37], v[110:113], v[164:167], v[34:37]
	v_mfma_f32_16x16x32_bf16 v[30:33], v[114:117], v[164:167], v[30:33]
	v_mfma_f32_16x16x32_bf16 v[22:25], v[118:121], v[164:167], v[22:25]
	ds_read_b128 v[164:167], v126 offset:23552
	s_waitcnt lgkmcnt(5)
	v_mfma_f32_16x16x32_bf16 v[38:41], v[106:109], v[168:171], v[38:41]
	v_mfma_f32_16x16x32_bf16 v[14:17], v[110:113], v[168:171], v[14:17]
	v_mfma_f32_16x16x32_bf16 v[10:13], v[114:117], v[168:171], v[10:13]
	v_mfma_f32_16x16x32_bf16 v[6:9], v[118:121], v[168:171], v[6:9]
	ds_read_b128 v[168:171], v127 offset:1024
	s_waitcnt lgkmcnt(5)
	v_mfma_f32_16x16x32_bf16 v[42:45], v[106:109], v[234:237], v[42:45]
	ds_read_b128 v[106:109], v127 offset:3072
	v_mfma_f32_16x16x32_bf16 v[18:21], v[110:113], v[234:237], v[18:21]
	ds_read_b128 v[110:113], v127 offset:5120
	v_mfma_f32_16x16x32_bf16 v[26:29], v[114:117], v[234:237], v[26:29]
	ds_read_b128 v[114:117], v127 offset:7168
	v_mfma_f32_16x16x32_bf16 v[2:5], v[118:121], v[234:237], v[2:5]
	s_waitcnt lgkmcnt(3)
	v_mfma_f32_16x16x32_bf16 v[46:49], v[238:241], v[168:171], v[46:49]
	v_mfma_f32_16x16x32_bf16 v[50:53], v[250:253], v[168:171], v[50:53]
	v_mfma_f32_16x16x32_bf16 v[58:61], v[122:125], v[168:171], v[58:61]
	v_mfma_f32_16x16x32_bf16 v[62:65], v[164:167], v[168:171], v[62:65]
	s_waitcnt lgkmcnt(2)
	v_mfma_f32_16x16x32_bf16 v[54:57], v[238:241], v[106:109], v[54:57]
	v_mfma_f32_16x16x32_bf16 v[34:37], v[250:253], v[106:109], v[34:37]
	v_mfma_f32_16x16x32_bf16 v[30:33], v[122:125], v[106:109], v[30:33]
	v_mfma_f32_16x16x32_bf16 v[22:25], v[164:167], v[106:109], v[22:25]
	s_waitcnt lgkmcnt(1)
	v_mfma_f32_16x16x32_bf16 v[38:41], v[238:241], v[110:113], v[38:41]
	v_mfma_f32_16x16x32_bf16 v[14:17], v[250:253], v[110:113], v[14:17]
	v_mfma_f32_16x16x32_bf16 v[10:13], v[122:125], v[110:113], v[10:13]
	v_mfma_f32_16x16x32_bf16 v[6:9], v[164:167], v[110:113], v[6:9]
	s_waitcnt lgkmcnt(0)
	v_mfma_f32_16x16x32_bf16 v[42:45], v[238:241], v[114:117], v[42:45]
	v_mfma_f32_16x16x32_bf16 v[18:21], v[250:253], v[114:117], v[18:21]
	v_mfma_f32_16x16x32_bf16 v[26:29], v[122:125], v[114:117], v[26:29]
	v_mfma_f32_16x16x32_bf16 v[2:5], v[164:167], v[114:117], v[2:5]
	s_cbranch_scc1 .LBB0_65
